# speedup vs baseline: 1.0138x; 1.0138x over previous
; __device__ __forceinline__ unsigned cvt_pk(float lo, float hi) { unsigned r; asm("v_cvt_pk_bf16_f32 %0, %1, %2" : "=v"(r) : "v"(lo), "v"(hi)); return r; }
; __device__ __forceinline__ int uni(int x) { return __builtin_amdgcn_readfirstlane(x); }
; __device__ __forceinline__ void sp_load(const Params& p, int item, int tid, u32x2 (&wreg)[8], unsigned (&vreg)[32]) {
;     ...
;     const float* wsp = p.in[15] + (size_t)g * 16384;
; #pragma unroll
;     for (int ii = 0; ii < 8; ++ii) { const int pc = tid + 512 * ii, t = pc >> 5, s4 = (pc & 31) * 4; const f32x4 wv = *(const f32x4*)(wsp + t * 128 + s4); float x[4];
; #pragma unroll
;         for (int j = 0; j < 4; ++j) x[j] = (s4 + j <= t && t < L) ? wv[j] : 0.f;
;         wreg[ii].x = cvt_pk(x[0], x[1]); wreg[ii].y = cvt_pk(x[2], x[3]); }
;     const int ch = tid & 255, sh = uni(tid >> 8);
;     const bf16_t* vp = VLN + (size_t)(row0 + sh * 64) * D + g * 256;
; #pragma unroll
;     for (int q = 0; q < 32; ++q) { const int s = sh * 64 + 2 * q; unsigned lo = 0u, hi = 0u;
;         if (s < L) { lo = vp[(2 * q) * D + ch]; hi = vp[(2 * q + 1) * D + ch]; }
.LBB0_1522:
	s_and_b32 s33, s61, 7
	s_lshl_b32 s20, s33, 16
	v_lshl_add_u64 v[2:3], v[130:131], 0, s[20:21]
	v_lshl_add_u64 v[4:5], v[112:113], 2, v[2:3]
	global_load_dwordx4 v[214:217], v[4:5], off
	v_lshl_add_u64 v[4:5], v[114:115], 2, v[2:3]
	global_load_dwordx4 v[218:221], v[4:5], off
	v_lshl_add_u64 v[4:5], v[116:117], 2, v[2:3]
	global_load_dwordx4 v[222:225], v[4:5], off
	v_lshl_add_u64 v[4:5], v[118:119], 2, v[2:3]
	global_load_dwordx4 v[226:229], v[4:5], off
	v_lshl_add_u64 v[4:5], v[120:121], 2, v[2:3]
	global_load_dwordx4 v[230:233], v[4:5], off
	v_lshl_add_u64 v[4:5], v[122:123], 2, v[2:3]
	global_load_dwordx4 v[234:237], v[4:5], off
	v_lshl_add_u64 v[4:5], v[124:125], 2, v[2:3]
	global_load_dwordx4 v[238:241], v[4:5], off
	v_lshl_add_u64 v[4:5], v[126:127], 2, v[2:3]
	global_load_dwordx4 v[242:245], v[4:5], off
	v_cmp_gt_i32_e64 s[4:5], s17, v136
	s_and_b64 vcc, s[64:65], s[4:5]
	s_waitcnt vmcnt(7)
	v_cndmask_b32_e32 v0, 0, v214, vcc
	s_and_b64 vcc, s[66:67], s[4:5]
	v_cndmask_b32_e32 v4, 0, v215, vcc
	s_and_b64 vcc, s[68:69], s[4:5]
	v_cndmask_b32_e32 v5, 0, v216, vcc
	s_and_b64 vcc, s[26:27], s[4:5]
	v_cndmask_b32_e32 v6, 0, v217, vcc
	v_cvt_pk_bf16_f32 v94, v0, v4
	v_cvt_pk_bf16_f32 v95, v5, v6
	v_cmp_gt_i32_e32 vcc, s17, v137
	s_and_b64 s[4:5], s[30:31], vcc
	s_waitcnt vmcnt(6)
	v_cndmask_b32_e64 v0, 0, v218, s[4:5]
	s_and_b64 s[4:5], s[70:71], vcc
	v_cndmask_b32_e64 v4, 0, v219, s[4:5]
	s_and_b64 s[4:5], s[72:73], vcc
	v_cndmask_b32_e64 v5, 0, v220, s[4:5]
	s_and_b64 vcc, s[74:75], vcc
	v_cndmask_b32_e32 v6, 0, v221, vcc
	v_cvt_pk_bf16_f32 v96, v0, v4
	v_cvt_pk_bf16_f32 v97, v5, v6
	v_cmp_gt_i32_e32 vcc, s17, v138
	s_and_b64 s[4:5], s[76:77], vcc
	s_waitcnt vmcnt(5)
	v_cndmask_b32_e64 v0, 0, v222, s[4:5]
	s_and_b64 s[4:5], s[78:79], vcc
	v_cndmask_b32_e64 v4, 0, v223, s[4:5]
	s_and_b64 s[4:5], s[80:81], vcc
	v_cndmask_b32_e64 v5, 0, v224, s[4:5]
	s_and_b64 vcc, s[82:83], vcc
	v_cndmask_b32_e32 v6, 0, v225, vcc
	v_cvt_pk_bf16_f32 v98, v0, v4
	v_cvt_pk_bf16_f32 v99, v5, v6
	v_cmp_gt_i32_e32 vcc, s17, v139
	s_and_b64 s[4:5], s[84:85], vcc
	s_waitcnt vmcnt(4)
	v_cndmask_b32_e64 v0, 0, v226, s[4:5]
	s_and_b64 s[4:5], s[18:19], vcc
	v_cndmask_b32_e64 v4, 0, v227, s[4:5]
	s_and_b64 s[4:5], s[56:57], vcc
	v_cndmask_b32_e64 v5, 0, v228, s[4:5]
	s_and_b64 vcc, s[86:87], vcc
	v_cndmask_b32_e32 v6, 0, v229, vcc
	v_cvt_pk_bf16_f32 v100, v0, v4
	v_cvt_pk_bf16_f32 v101, v5, v6
	v_cmp_gt_i32_e32 vcc, s17, v140
	s_and_b64 s[4:5], s[2:3], vcc
	s_waitcnt vmcnt(3)
	v_cndmask_b32_e64 v0, 0, v230, s[4:5]
	s_and_b64 s[4:5], s[88:89], vcc
	v_cndmask_b32_e64 v4, 0, v231, s[4:5]
	s_and_b64 s[4:5], s[90:91], vcc
	v_cndmask_b32_e64 v5, 0, v232, s[4:5]
	s_and_b64 vcc, s[96:97], vcc
	v_cndmask_b32_e32 v6, 0, v233, vcc
	v_cvt_pk_bf16_f32 v102, v0, v4
	v_cvt_pk_bf16_f32 v103, v5, v6
	v_readlane_b32 s4, v254, 63
	v_cmp_gt_i32_e32 vcc, s17, v141
	v_readlane_b32 s5, v255, 0
	s_and_b64 s[4:5], s[4:5], vcc
	s_waitcnt vmcnt(2)
	v_cndmask_b32_e64 v0, 0, v234, s[4:5]
	v_readlane_b32 s4, v255, 1
	v_readlane_b32 s5, v255, 2
	s_and_b64 s[4:5], s[4:5], vcc
	s_nop 0
	v_cndmask_b32_e64 v4, 0, v235, s[4:5]
	v_readlane_b32 s4, v255, 3
	v_readlane_b32 s5, v255, 4
	s_and_b64 s[4:5], s[4:5], vcc
	v_cvt_pk_bf16_f32 v104, v0, v4
	s_nop 0
	v_cndmask_b32_e64 v5, 0, v236, s[4:5]
	v_readlane_b32 s4, v255, 5
	v_readlane_b32 s5, v255, 6
	s_and_b64 vcc, s[4:5], vcc
	v_cndmask_b32_e32 v6, 0, v237, vcc
	v_cvt_pk_bf16_f32 v105, v5, v6
	v_readlane_b32 s4, v255, 7
	v_cmp_gt_i32_e32 vcc, s17, v142
	v_readlane_b32 s5, v255, 8
	s_and_b64 s[4:5], s[4:5], vcc
	s_waitcnt vmcnt(1)
	v_cndmask_b32_e64 v0, 0, v238, s[4:5]
	v_readlane_b32 s4, v255, 9
	v_readlane_b32 s5, v255, 10
	s_and_b64 s[4:5], s[4:5], vcc
	s_nop 0
	v_cndmask_b32_e64 v4, 0, v239, s[4:5]
	v_readlane_b32 s4, v255, 11
	v_readlane_b32 s5, v255, 12
	s_and_b64 s[4:5], s[4:5], vcc
	v_cvt_pk_bf16_f32 v106, v0, v4
	s_nop 0
	v_cndmask_b32_e64 v5, 0, v240, s[4:5]
	v_readlane_b32 s4, v255, 13
	v_readlane_b32 s5, v255, 14
	s_and_b64 vcc, s[4:5], vcc
	v_cndmask_b32_e32 v6, 0, v241, vcc
	v_cvt_pk_bf16_f32 v107, v5, v6
	v_readlane_b32 s4, v255, 15
	v_cmp_gt_i32_e32 vcc, s17, v143
	v_readlane_b32 s5, v255, 16
	s_and_b64 s[4:5], s[4:5], vcc
	s_waitcnt vmcnt(0)
	v_cndmask_b32_e64 v0, 0, v242, s[4:5]
	v_readlane_b32 s4, v255, 17
	v_readlane_b32 s5, v255, 18
	s_and_b64 s[4:5], s[4:5], vcc
	s_nop 0
	v_cndmask_b32_e64 v2, 0, v243, s[4:5]
	v_readlane_b32 s4, v255, 19
	v_readlane_b32 s5, v255, 20
	s_and_b64 s[4:5], s[4:5], vcc
	v_cvt_pk_bf16_f32 v108, v0, v2
	v_lshlrev_b32_e32 v0, 1, v110
	v_cndmask_b32_e64 v3, 0, v244, s[4:5]
	v_readlane_b32 s4, v255, 21
	v_readlane_b32 s5, v255, 22
	s_and_b64 vcc, s[4:5], vcc
	v_readfirstlane_b32 s4, v111
	s_ashr_i32 s4, s4, 2
	s_and_b32 s20, s4, 0xffffffc0
	s_add_i32 s4, s20, s15
	s_ashr_i32 s5, s4, 31
	s_lshl_b64 s[4:5], s[4:5], 12
	s_add_u32 s4, s92, s4
	v_readlane_b32 s15, v252, 27
	s_addc_u32 s5, s15, s5
	s_lshl_b32 s15, s33, 9
	s_add_u32 s4, s4, s15
	s_addc_u32 s5, s5, 0
	s_sub_i32 s15, s17, s20
	v_cndmask_b32_e32 v4, 0, v245, vcc
	v_cvt_pk_bf16_f32 v109, v3, v4
	v_mov_b32_e32 v3, 0
	s_cmp_gt_i32 s15, 63
	s_cbranch_scc1 .Lmy_spl_fast
	s_cmp_lt_i32 s15, 1
	v_mov_b32_e32 v2, 0
	s_cbranch_scc1 .LBB0_1524
	v_lshl_add_u64 v[4:5], s[4:5], 0, v[0:1]
	v_add_co_u32_e32 v4, vcc, 0x1000, v4
	s_nop 1
	v_addc_co_u32_e32 v5, vcc, 0, v5, vcc
	global_load_ushort v2, v0, s[4:5]
	s_nop 0
	global_load_ushort v4, v[4:5], off
	s_waitcnt vmcnt(0)
	v_lshl_or_b32 v2, v4, 16, v2

; __device__ __forceinline__ int uni(int x) { return __builtin_amdgcn_readfirstlane(x); }
; __device__ __forceinline__ void sp_load(const Params& p, int item, int tid, u32x2 (&wreg)[8], unsigned (&vreg)[32]) {
;     ...
;     const int ch = tid & 255, sh = uni(tid >> 8);
;     const bf16_t* vp = VLN + (size_t)(row0 + sh * 64) * D + g * 256;
; #pragma unroll
;     for (int q = 0; q < 32; ++q) { const int s = sh * 64 + 2 * q; unsigned lo = 0u, hi = 0u;
;         if (s < L) { lo = vp[(2 * q) * D + ch]; hi = vp[(2 * q + 1) * D + ch]; }
;         vreg[q] = lo | (hi << 16);
;         if ((q & 7) == 7) asm volatile("" ::: "memory"); }
.Lmy_spl_fast:
	s_add_u32 s4, s4, 0x1000
	s_addc_u32 s5, s5, 0
	global_load_ushort v2, v0, s[4:5] offset:-4096
	global_load_ushort v214, v0, s[4:5]
	s_add_u32 s4, s4, 0x2000
	s_addc_u32 s5, s5, 0
	global_load_ushort v3, v0, s[4:5] offset:-4096
	global_load_ushort v215, v0, s[4:5]
	s_add_u32 s4, s4, 0x2000
	s_addc_u32 s5, s5, 0
	global_load_ushort v4, v0, s[4:5] offset:-4096
	global_load_ushort v216, v0, s[4:5]
	s_add_u32 s4, s4, 0x2000
	s_addc_u32 s5, s5, 0
	global_load_ushort v5, v0, s[4:5] offset:-4096
	global_load_ushort v217, v0, s[4:5]
	s_add_u32 s4, s4, 0x2000
	s_addc_u32 s5, s5, 0
	global_load_ushort v6, v0, s[4:5] offset:-4096
	global_load_ushort v218, v0, s[4:5]
	s_add_u32 s4, s4, 0x2000
	s_addc_u32 s5, s5, 0
	global_load_ushort v7, v0, s[4:5] offset:-4096
	global_load_ushort v219, v0, s[4:5]
	s_add_u32 s4, s4, 0x2000
	s_addc_u32 s5, s5, 0
	global_load_ushort v8, v0, s[4:5] offset:-4096
	global_load_ushort v220, v0, s[4:5]
	s_add_u32 s4, s4, 0x2000
	s_addc_u32 s5, s5, 0
	global_load_ushort v9, v0, s[4:5] offset:-4096
	global_load_ushort v221, v0, s[4:5]
	s_add_u32 s4, s4, 0x2000
	s_addc_u32 s5, s5, 0
	global_load_ushort v10, v0, s[4:5] offset:-4096
	global_load_ushort v222, v0, s[4:5]
	s_add_u32 s4, s4, 0x2000
	s_addc_u32 s5, s5, 0
	global_load_ushort v11, v0, s[4:5] offset:-4096
	global_load_ushort v223, v0, s[4:5]
	s_add_u32 s4, s4, 0x2000
	s_addc_u32 s5, s5, 0
	global_load_ushort v12, v0, s[4:5] offset:-4096
	global_load_ushort v224, v0, s[4:5]
	s_add_u32 s4, s4, 0x2000
	s_addc_u32 s5, s5, 0
	global_load_ushort v13, v0, s[4:5] offset:-4096
	global_load_ushort v225, v0, s[4:5]
	s_add_u32 s4, s4, 0x2000
	s_addc_u32 s5, s5, 0
	global_load_ushort v14, v0, s[4:5] offset:-4096
	global_load_ushort v226, v0, s[4:5]
	s_add_u32 s4, s4, 0x2000
	s_addc_u32 s5, s5, 0
	global_load_ushort v15, v0, s[4:5] offset:-4096
	global_load_ushort v227, v0, s[4:5]
	s_add_u32 s4, s4, 0x2000
	s_addc_u32 s5, s5, 0
	global_load_ushort v16, v0, s[4:5] offset:-4096
	global_load_ushort v228, v0, s[4:5]
	s_add_u32 s4, s4, 0x2000
	s_addc_u32 s5, s5, 0
	global_load_ushort v17, v0, s[4:5] offset:-4096
	global_load_ushort v229, v0, s[4:5]
	s_add_u32 s4, s4, 0x2000
	s_addc_u32 s5, s5, 0
	global_load_ushort v18, v0, s[4:5] offset:-4096
	global_load_ushort v230, v0, s[4:5]
	s_add_u32 s4, s4, 0x2000
	s_addc_u32 s5, s5, 0
	global_load_ushort v19, v0, s[4:5] offset:-4096
	global_load_ushort v231, v0, s[4:5]
	s_add_u32 s4, s4, 0x2000
	s_addc_u32 s5, s5, 0
	global_load_ushort v20, v0, s[4:5] offset:-4096
	global_load_ushort v232, v0, s[4:5]
	s_add_u32 s4, s4, 0x2000
	s_addc_u32 s5, s5, 0
	global_load_ushort v21, v0, s[4:5] offset:-4096
	global_load_ushort v233, v0, s[4:5]
	s_add_u32 s4, s4, 0x2000
	s_addc_u32 s5, s5, 0
	global_load_ushort v22, v0, s[4:5] offset:-4096
	global_load_ushort v234, v0, s[4:5]
	s_add_u32 s4, s4, 0x2000
	s_addc_u32 s5, s5, 0
	global_load_ushort v23, v0, s[4:5] offset:-4096
	global_load_ushort v235, v0, s[4:5]
	s_add_u32 s4, s4, 0x2000
	s_addc_u32 s5, s5, 0
	global_load_ushort v24, v0, s[4:5] offset:-4096
	global_load_ushort v236, v0, s[4:5]
	s_add_u32 s4, s4, 0x2000
	s_addc_u32 s5, s5, 0
	global_load_ushort v25, v0, s[4:5] offset:-4096
	global_load_ushort v237, v0, s[4:5]
	s_add_u32 s4, s4, 0x2000
	s_addc_u32 s5, s5, 0
	global_load_ushort v26, v0, s[4:5] offset:-4096
	global_load_ushort v238, v0, s[4:5]
	s_add_u32 s4, s4, 0x2000
	s_addc_u32 s5, s5, 0
	global_load_ushort v27, v0, s[4:5] offset:-4096
	global_load_ushort v239, v0, s[4:5]
	s_add_u32 s4, s4, 0x2000
	s_addc_u32 s5, s5, 0
	global_load_ushort v28, v0, s[4:5] offset:-4096
	global_load_ushort v240, v0, s[4:5]
	s_add_u32 s4, s4, 0x2000
	s_addc_u32 s5, s5, 0
	global_load_ushort v29, v0, s[4:5] offset:-4096
	global_load_ushort v241, v0, s[4:5]
	s_add_u32 s4, s4, 0x2000
	s_addc_u32 s5, s5, 0
	global_load_ushort v30, v0, s[4:5] offset:-4096
	global_load_ushort v242, v0, s[4:5]
	s_add_u32 s4, s4, 0x2000
	s_addc_u32 s5, s5, 0
	global_load_ushort v31, v0, s[4:5] offset:-4096
	global_load_ushort v243, v0, s[4:5]
	s_waitcnt vmcnt(28)
	v_lshl_or_b32 v2, v214, 16, v2
	v_lshl_or_b32 v3, v215, 16, v3
	v_lshl_or_b32 v4, v216, 16, v4
	v_lshl_or_b32 v5, v217, 16, v5
	v_lshl_or_b32 v6, v218, 16, v6
	v_lshl_or_b32 v7, v219, 16, v7
	v_lshl_or_b32 v8, v220, 16, v8
	v_lshl_or_b32 v9, v221, 16, v9
	v_lshl_or_b32 v10, v222, 16, v10
	v_lshl_or_b32 v11, v223, 16, v11
	v_lshl_or_b32 v12, v224, 16, v12
	v_lshl_or_b32 v13, v225, 16, v13
	v_lshl_or_b32 v14, v226, 16, v14
	v_lshl_or_b32 v15, v227, 16, v15
	v_lshl_or_b32 v16, v228, 16, v16
	v_lshl_or_b32 v17, v229, 16, v17
	s_add_u32 s4, s4, 0x2000
	s_addc_u32 s5, s5, 0
	global_load_ushort v32, v0, s[4:5] offset:-4096
	global_load_ushort v244, v0, s[4:5]
	s_add_u32 s4, s4, 0x2000
	s_addc_u32 s5, s5, 0
	global_load_ushort v33, v0, s[4:5] offset:-4096
	global_load_ushort v245, v0, s[4:5]
	s_waitcnt vmcnt(0)
	v_lshl_or_b32 v18, v230, 16, v18
	v_lshl_or_b32 v19, v231, 16, v19
	v_lshl_or_b32 v20, v232, 16, v20
	v_lshl_or_b32 v21, v233, 16, v21
	v_lshl_or_b32 v22, v234, 16, v22
	v_lshl_or_b32 v23, v235, 16, v23
	v_lshl_or_b32 v24, v236, 16, v24
	v_lshl_or_b32 v25, v237, 16, v25
	v_lshl_or_b32 v26, v238, 16, v26
	v_lshl_or_b32 v27, v239, 16, v27
	v_lshl_or_b32 v28, v240, 16, v28
	v_lshl_or_b32 v29, v241, 16, v29
	v_lshl_or_b32 v30, v242, 16, v30
	v_lshl_or_b32 v31, v243, 16, v31
	v_lshl_or_b32 v32, v244, 16, v32
	v_lshl_or_b32 v33, v245, 16, v33
	s_branch .LBB0_1586
